# attention work list: long MLA items split at tuned unequal key-tile boundaries, list ordered by falling piece size (tighter longest-first packing)
# speedup vs baseline: 1.0070x; 1.0028x over previous
; #define LAS __attribute__((address_space(3)))
; template <int TYPE>
; __device__ __forceinline__ void attn_item(const Params& p, int layer, int head, int qb, int mode, LAS unsigned char* lds) {
;     ...
;     bf16x8 qr[NQ];
; #pragma unroll
;     for (int d0 = 0; d0 < NQ; ++d0) qr[d0] = *(const bf16x8*)(Qb + (size_t)qrow * ldq + d0 * 16 + hi * 8);
;     LAS unsigned char* V_lds = lds; LAS unsigned char* K_lds = lds + OFF_K; LAS float* B_lds = (LAS float*)(lds + OFF_B);
;     LAS float* wsl = (LAS float*)(lds + LDS_BYTES - 4096) + wid * 64;
;     const int vb0 = (int)(unsigned)(uintptr_t)V_lds + v_rd_base(lane);
;     unsigned offK[2], offV[2], offR;
; #pragma unroll
;     for (int j = 0; j < 2; ++j) {
;         const int row = (j * 8 + wid) * 4 + (lane >> 4), ch = (lane & 15) ^ (row & 7);
;         offK[j] = (unsigned)(row * ldk + ch * 8) * 2u;
;         const int q = (j * 8 + wid) * 64 + lane, sub = q >> 5, kk = (sub >> 2) * 8 + ((q & 31) >> 2), c = (sub & 3) * 32 + (q & 3) * 8;
;         const int k = (kk & ~0xC) | ((kk & 4) << 1) | ((kk & 8) >> 1);
;         offV[j] = (unsigned)(k * ldv + c) * 2u;
;     }
;     { const int row = wid * 8 + (lane >> 3), ch = (lane & 7) ^ (row & 7); offR = (unsigned)(row * 64 + ch * 8) * 2u; }
;     ...
;     float m_reg = -1e30f, l_reg = 0.f; f32x16 o[4];
; #pragma unroll
;     for (int d = 0; d < 4; ++d) o[d] = (f32x16){};
;     constexpr int T0 = PADR / 64;
;     int tbeg = T0; float Bb = 0.f;
;     if (TYPE == 1) {
;         const float* gq = p.in[I_GFQ] + layer * 128; const float* gk = p.in[I_GFK] + layer * 128;
;         float gm = fmaxf(fabsf(gq[lane] * gk[lane]), fabsf(gq[lane + 64] * gk[lane + 64]));
; #pragma unroll
;         for (int o_ = 32; o_ >= 1; o_ >>= 1) gm = fmaxf(gm, __shfl_xor(gm, o_));
;         Bb = gm * 11.313708498984761f * LOG2E * 1.02f;
;     }
;     int tend = NT;
; __device__ __forceinline__ void phase_attn(const Params& p, int layer, LAS unsigned char* lds) {
;     ...
;     for (;;) {
;         if (opaque_tid() == 0) *sitem = atomicAdd(ctr, 1);
;         __syncthreads();
;         const int it = *sitem;
;         __syncthreads();
;         if (it >= 464 + 264) break;
;         if (it < 264) attn_item<1>(p, layer, it & 7, 32 - (it >> 3), 0, lds);
;         else { const int e = MLA_ORDER[(it - 264) >> 3]; attn_item<0>(p, layer, it & 7, e & 63, e >> 6, lds); }
.LBB0_813:
	s_or_b64 exec, exec, s[0:1]
	v_readlane_b32 s0, v254, 10
	s_waitcnt vmcnt(0) lgkmcnt(0)
	s_barrier
	v_mov_b32_e32 v0, s0
	ds_read_b32 v0, v0
	s_movk_i32 s0, 0x2d7
	s_waitcnt lgkmcnt(0)
	s_barrier
	v_cmp_lt_i32_e32 vcc, s0, v0
	v_readfirstlane_b32 s42, v0
	s_mov_b64 s[0:1], -1
	s_cbranch_vccnz .LBB0_810
	s_cmpk_gt_i32 s42, 0x107
	s_cbranch_scc0 .LBB0_842
	s_add_i32 s0, s42, 0xfffffef8
	s_lshr_b32 s2, s0, 3
	s_getpc_b64 s[0:1]
	s_add_u32 s0, s0, MLA_ORDER@rel32@lo+4
	s_addc_u32 s1, s1, MLA_ORDER@rel32@hi+12
	v_mov_b32_e32 v0, s2
	global_load_sbyte v9, v0, s[0:1]
	global_load_ubyte v18, v0, s[0:1] offset:64
	v_mov_b32_e32 v2, v210
	s_and_b32 s5, s42, 7
	v_readfirstlane_b32 s6, v2
	s_ashr_i32 s13, s6, 6
	s_lshl_b32 s4, s13, 5
	s_mul_i32 s3, s5, 0x180
	v_and_b32_e32 v226, 31, v2
	v_and_b32_e32 v227, 63, v2
	v_lshlrev_b32_e32 v5, 3, v2
	v_bfe_u32 v225, v2, 5, 1
	v_bfe_u32 v223, v2, 4, 2
	v_and_b32_e32 v5, 24, v5
	s_movk_i32 s30, 0x60
	v_lshrrev_b32_e32 v6, 1, v2
	v_lshlrev_b32_e32 v0, 4, v225
	v_and_b32_e32 v224, 15, v2
	v_bfe_u32 v3, v2, 2, 2
	v_and_b32_e32 v4, 32, v2
	v_and_b32_e32 v6, 8, v6
	v_or_b32_e32 v13, v6, v3
	s_mov_b64 s[36:37], 0x100
	v_bfe_u32 v7, v2, 3, 3
	v_bitop3_b32 v8, v7, v2, 7 bitop3:0x78
	v_lshlrev_b32_e32 v7, 7, v7
	v_lshlrev_b32_e32 v8, 4, v8
	s_waitcnt vmcnt(0)
	v_readfirstlane_b32 s1, v9
	v_readfirstlane_b32 s100, v18
	s_and_b32 s25, s1, 63
	s_lshl_b32 s2, s25, 8
	s_and_b32 s0, s1, 0xff
	s_bfe_u32 s24, s1, 0x20006
	s_add_i32 s2, s4, s2
	s_add_u32 s10, s21, s3
	v_readlane_b32 s3, v254, 60
	s_addc_u32 s11, s3, 0
	v_or_b32_e32 v9, s2, v226
	s_lshl_b32 s19, s5, 9
	v_readlane_b32 s3, v254, 61
	v_mov_b64_e32 v[10:11], s[10:11]
	s_movk_i32 s11, 0xc00
	s_add_u32 s7, s3, s19
	v_readlane_b32 s3, v254, 62
	v_mad_i64_i32 v[10:11], s[28:29], v9, s11, v[10:11]
	s_addc_u32 s10, s3, 0
	s_lshl_b32 s3, s25, 2
	s_and_b32 s28, s6, 0x3fffffc0
	s_lshl_b32 s14, s13, 1
	s_add_i32 s29, s13, 8
	s_lshl_b32 s12, s13, 2
	s_and_b32 s11, s6, 64
	s_add_i32 s6, s3, 4
	s_and_b32 s18, s14, 4
	s_lshl_b32 s3, s29, 2
	v_lshl_or_b32 v14, s29, 6, v227
	s_lshl_b32 s14, s29, 1
	s_lshl_b32 s28, s28, 2
	v_or_b32_e32 v12, s12, v223
	s_and_b32 s12, s12, 0xffff0
	v_or_b32_e32 v15, s3, v223
	v_and_or_b32 v14, v14, s30, v5
	s_and_b32 s30, s3, 0xffff0
	s_and_b32 s31, s14, 4
	s_add_i32 s3, s28, 0
	v_lshl_add_u64 v[10:11], v[10:11], 0, v[0:1]
	s_or_b32 s29, s12, s18
	s_or_b32 s14, s30, s31
	s_add_i32 s3, s3, 0x1f000
	v_or3_b32 v9, v4, s11, v5
	global_load_dwordx4 v[130:133], v[10:11], off
	global_load_dwordx4 v[134:137], v[10:11], off offset:32
	global_load_dwordx4 v[138:141], v[10:11], off offset:64
	global_load_dwordx4 v[142:145], v[10:11], off offset:96
	global_load_dwordx4 v[146:149], v[10:11], off offset:128
	global_load_dwordx4 v[150:153], v[10:11], off offset:160
	global_load_dwordx4 v[154:157], v[10:11], off offset:192
	global_load_dwordx4 v[158:161], v[10:11], off offset:224
	global_load_dwordx4 v[162:165], v[10:11], off offset:256
	global_load_dwordx4 v[166:169], v[10:11], off offset:288
	global_load_dwordx4 v[170:173], v[10:11], off offset:320
	global_load_dwordx4 v[174:177], v[10:11], off offset:352
	v_bitop3_b32 v10, v12, v224, 7 bitop3:0x6c
	s_cmp_lt_u32 s25, 33
	v_lshlrev_b32_e32 v11, 1, v9
	v_lshlrev_b32_e32 v9, 4, v10
	v_or_b32_e32 v10, s29, v13
	s_cselect_b32 s33, s6, 0x84
	v_lshl_or_b32 v17, v12, 12, v9
	v_lshl_or_b32 v12, v10, 12, v11
	v_or_b32_e32 v11, s14, v13
	s_mov_b32 s14, s100
	s_lshl_b32 s6, s13, 10
	s_nop 0
	s_cmp_eq_u32 s24, 1
	s_sext_i32_i16 s1, s1
	s_cselect_b32 s40, s14, s33
	s_cmp_lt_i32 s1, 0
	s_cselect_b32 s14, s14, 3
	s_lshl_b64 s[38:39], s[14:15], 18
	s_add_u32 s28, s7, s38
	s_addc_u32 s29, s10, s39
	s_and_b32 s1, s14, 1
	s_mul_i32 s7, s1, 0x6000
	s_add_i32 s7, s7, 0
	s_lshl_b32 s1, s1, 13
	s_add_i32 s7, s7, s6
	v_mov_b32_e32 v13, v1
	v_bitop3_b32 v16, v15, v224, 7 bitop3:0x6c
	s_add_i32 m0, s7, 0x8000
	v_lshl_add_u64 v[12:13], s[28:29], 0, v[12:13]
	s_sub_i32 s1, s7, s1
	v_lshlrev_b32_e32 v10, 4, v16
	global_load_lds_dwordx4 v17, s[28:29]
	v_lshl_add_u64 v[12:13], v[12:13], 0, s[36:37]
	s_mov_b32 m0, s1
	v_lshlrev_b32_e32 v14, 1, v14
	v_lshl_or_b32 v15, v15, 12, v10
	global_load_lds_dwordx4 v[12:13], off
	s_add_i32 m0, s7, 0xa000
	v_lshl_or_b32 v14, v11, 12, v14
	global_load_lds_dwordx4 v15, s[28:29]
	v_mov_b32_e32 v15, v1
	s_add_i32 m0, s1, 0x2000
	v_lshl_add_u64 v[12:13], s[28:29], 0, v[14:15]
	s_cmp_gt_u32 s0, 63
	v_lshl_add_u64 v[12:13], v[12:13], 0, s[36:37]
	s_cselect_b64 s[36:37], -1, 0
	s_cmp_lt_u32 s0, 64
	s_cselect_b32 s7, s33, s40
	s_lshl_b64 s[40:41], s[14:15], 13
	v_readlane_b32 s0, v254, 63
	s_add_u32 s0, s0, s40
	v_readlane_b32 s1, v255, 0
	s_addc_u32 s1, s1, s41
	s_bitcmp1_b32 s14, 0
	s_cselect_b32 s10, 0x6000, 0
	s_add_i32 s10, s10, 0
	s_add_i32 s10, s10, s6
	v_or3_b32 v11, v8, v7, s6
	global_load_lds_dwordx4 v[12:13], off
	s_add_i32 m0, s10, 0xc000
	s_sub_i32 s7, s7, s14
	global_load_lds_dwordx4 v11, s[0:1]
	s_waitcnt vmcnt(0)
	s_cmp_lt_i32 s7, 1
	v_cmp_gt_u32_e64 s[0:1], 32, v227
	s_waitcnt vmcnt(0) lgkmcnt(0)
	s_barrier
; #define LAS __attribute__((address_space(3)))
; template <int TYPE>
; __device__ __forceinline__ void attn_item(const Params& p, int layer, int head, int qb, int mode, LAS unsigned char* lds) {
;     ...
;     unsigned offK[2], offV[2], offR;
; #pragma unroll
;     for (int j = 0; j < 2; ++j) {
;         const int row = (j * 8 + wid) * 4 + (lane >> 4), ch = (lane & 15) ^ (row & 7);
;         offK[j] = (unsigned)(row * ldk + ch * 8) * 2u;
;         const int q = (j * 8 + wid) * 64 + lane, sub = q >> 5, kk = (sub >> 2) * 8 + ((q & 31) >> 2), c = (sub & 3) * 32 + (q & 3) * 8;
;         const int k = (kk & ~0xC) | ((kk & 4) << 1) | ((kk & 8) >> 1);
;         offV[j] = (unsigned)(k * ldv + c) * 2u;
;     }
;     { const int row = wid * 8 + (lane >> 3), ch = (lane & 7) ^ (row & 7); offR = (unsigned)(row * 64 + ch * 8) * 2u; }
;     ...
;     float m_reg = -1e30f, l_reg = 0.f; f32x16 o[4];
; #pragma unroll
;     for (int d = 0; d < 4; ++d) o[d] = (f32x16){};
;     constexpr int T0 = PADR / 64;
;     int tbeg = T0; float Bb = 0.f;
;     if (TYPE == 1) {
;         const float* gq = p.in[I_GFQ] + layer * 128; const float* gk = p.in[I_GFK] + layer * 128;
;         float gm = fmaxf(fabsf(gq[lane] * gk[lane]), fabsf(gq[lane + 64] * gk[lane + 64]));
; #pragma unroll
;         for (int o_ = 32; o_ >= 1; o_ >>= 1) gm = fmaxf(gm, __shfl_xor(gm, o_));
;         Bb = gm * 11.313708498984761f * LOG2E * 1.02f;
;     }
;     int tend = NT;
;     if (TYPE == 0 && mode != 0) { const int mid = (T0 + NT + 1) >> 1; if (mode == 1) tend = mid; else tbeg = mid; }
;     const int ntiles = tend - tbeg, tfirst = TYPE == 1 ? tend - 1 : tbeg;
;     LAS float* xm = (LAS float*)(lds + LDS_BYTES - 2048);
;     ADMA(tfirst, tfirst & 1);
;     asm volatile("s_waitcnt vmcnt(0)" ::: "memory");
;     __syncthreads();
;     int kb[4], kbr[4];
; #pragma unroll
;     for (int dd = 0; dd < 4; ++dd) { kb[dd] = r32 * 256 + ((((dd * 2 + hi) ^ (r32 & 7))) << 4); kbr[dd] = 16384 + r32 * 128 + ((((dd * 2 + hi) ^ (r32 & 7))) << 4); }
;     for (int it2 = 0; it2 < ntiles; ++it2) {
	s_cbranch_scc1 .LBB0_830
	v_lshlrev_b32_e32 v13, 4, v227
	v_lshlrev_b32_e32 v12, 3, v227
	v_and_b32_e32 v13, 0xc0, v13
	v_lshlrev_b32_e32 v14, 1, v227
	v_and_b32_e32 v11, 7, v2
	v_and_or_b32 v13, v12, 24, v13
	v_and_b32_e32 v14, 32, v14
	v_and_b32_e32 v12, 0x100, v12
	v_or3_b32 v12, v13, v14, v12
	v_xor_b32_e32 v13, v225, v11
	s_or_b32 s10, s2, 63
	v_lshlrev_b32_e32 v230, 4, v13
	v_bitop3_b32 v13, v225, v11, 2 bitop3:0x36
	v_lshlrev_b32_e32 v231, 4, v13
	v_bitop3_b32 v13, v225, v11, 4 bitop3:0x36
	s_add_u32 s28, s40, 0x27d62000
	v_lshlrev_b32_e32 v232, 4, v13
	v_add_u32_e32 v234, 0, v12
	s_addc_u32 s29, s41, 0
	v_add3_u32 v12, s6, v7, v8
	v_mov_b32_e32 v13, v1
	s_or_b32 s19, s38, s19
	v_lshl_add_u64 v[200:201], s[28:29], 0, v[12:13]
	s_add_u32 s28, s19, 0x25ca0100
	s_addc_u32 s29, s39, 0
	s_add_i32 s31, s31, s30
	s_lshl_b32 s30, s13, 6
	s_addk_i32 s30, 0x200
	v_or_b32_e32 v8, s30, v227
	v_add_u32_e32 v7, s31, v6
	v_lshlrev_b32_e32 v8, 1, v8
	v_and_b32_e32 v2, 3, v2
	v_add_lshl_u32 v7, v7, v3, 12
	v_and_b32_e32 v8, 0xc0, v8
	v_lshlrev_b32_e32 v2, 4, v2
	s_add_i32 s18, s18, s12
	v_or3_b32 v12, v7, v8, v2
	v_add3_u32 v2, s18, v6, v3
	v_add_u32_e32 v3, s11, v4
	s_add_u32 s18, s19, 0x25ca0000
	v_add_lshl_u32 v3, v3, v5, 1
	s_addc_u32 s19, s39, 0
	s_lshl_b32 s11, s13, 14
	v_lshl_or_b32 v2, v2, 12, v3
	v_mov_b32_e32 v3, v1
	s_add_i32 s12, s11, 0x20000
	v_lshlrev_b32_e32 v4, 12, v223
	v_lshl_add_u64 v[204:205], s[28:29], 0, v[2:3]
	v_or3_b32 v2, s12, v4, v10
	v_bitop3_b32 v11, v225, v11, 6 bitop3:0x36
	v_lshl_add_u64 v[206:207], s[18:19], 0, v[2:3]
	v_or3_b32 v2, s11, v4, v9
	v_mov_b32_e32 v16, v1
	v_mov_b32_e32 v17, v1
	v_lshlrev_b32_e32 v233, 4, v11
	v_lshl_add_u64 v[202:203], s[28:29], 0, v[12:13]
	v_lshl_add_u64 v[208:209], s[18:19], 0, v[2:3]
	v_mov_b32_e32 v2, v1
	v_mov_b32_e32 v4, v1
	v_mov_b32_e32 v5, v1
	v_mov_b32_e32 v6, v1
	v_mov_b32_e32 v7, v1
	v_mov_b32_e32 v8, v1
	v_mov_b32_e32 v9, v1
	v_mov_b32_e32 v10, v1
	v_mov_b32_e32 v11, v1
	v_mov_b32_e32 v12, v1
	v_mov_b32_e32 v14, v1
	v_mov_b32_e32 v15, v1
	v_mov_b64_e32 v[64:65], v[16:17]
	v_mov_b64_e32 v[48:49], v[16:17]
	v_mov_b64_e32 v[32:33], v[16:17]
	v_lshlrev_b32_e32 v228, 8, v226
	v_lshlrev_b32_e32 v229, 7, v226
	v_lshl_add_u32 v235, v226, 2, s3
	s_lshl_b32 s11, s14, 6
	s_mov_b32 s12, 0
	v_mov_b32_e32 v199, 0
	v_mov_b32_e32 v198, 0xf149f2ca
	v_add_u32_e32 v0, s3, v0
	v_mov_b64_e32 v[62:63], v[14:15]
	v_mov_b64_e32 v[60:61], v[12:13]
	v_mov_b64_e32 v[58:59], v[10:11]
	v_mov_b64_e32 v[56:57], v[8:9]
	v_mov_b64_e32 v[54:55], v[6:7]
	v_mov_b64_e32 v[52:53], v[4:5]
	v_mov_b64_e32 v[50:51], v[2:3]
	v_mov_b64_e32 v[46:47], v[14:15]
	v_mov_b64_e32 v[44:45], v[12:13]
	v_mov_b64_e32 v[42:43], v[10:11]
	v_mov_b64_e32 v[40:41], v[8:9]
	v_mov_b64_e32 v[38:39], v[6:7]
	v_mov_b64_e32 v[36:37], v[4:5]
	v_mov_b64_e32 v[34:35], v[2:3]
	v_mov_b64_e32 v[30:31], v[14:15]
	v_mov_b64_e32 v[28:29], v[12:13]
	v_mov_b64_e32 v[26:27], v[10:11]
	v_mov_b64_e32 v[24:25], v[8:9]
	v_mov_b64_e32 v[22:23], v[6:7]
	v_mov_b64_e32 v[20:21], v[4:5]
	v_mov_b64_e32 v[18:19], v[2:3]
	v_readlane_b32 s31, v254, 57
	v_readlane_b32 s30, v254, 23
	s_branch .LBB0_819

MLA_ORDER:
	.byte	93, 96, 88, 154, 92, 94, 159, 91, 160, 95, 148, 89, 158, 145, 151, 153, 157, 87, 86, 83, 85, 150, 156, 144, 149, 155, 146, 82, 90, 143, 147, 142, 7, 152, 77, 78, 84, 141, 79, 6, 76, 140, 80, 137, 139, 75, 5, 138, 74, 81, 136, 4, 72, 73, 3, 2, 1, 0
	.size	MLA_ORDER, 58
	.byte	0, 0, 0, 0, 0, 0
	.byte	73, 73, 72, 39, 72, 72, 59, 71, 73, 59, 30, 57, 72, 22, 49, 57, 73, 49, 48, 47, 47, 48, 72, 27, 47, 71, 39, 39, 39, 29, 47, 30, 0, 72, 30, 30, 30, 30, 29, 0, 28, 28, 27, 17, 25, 25, 0, 23, 23, 22, 18, 0, 18, 17, 0, 0, 0, 0
	.byte	0, 0, 0, 0, 0, 0

	.type	__hip_cuid_fbe44d3362ceab56,@object
